# layer-entry RMSNorm pass: next row's loads issued before the current row is reduced (software pipelined, one row ahead), sum of squares on packed pairs without register shuffles
# speedup vs baseline: 1.0064x; 1.0064x over previous
; __device__ __forceinline__ int otid() { int t = __builtin_amdgcn_workitem_id_x(); asm volatile("" : "+v"(t)); return t; }
; __device__ __forceinline__ int obid() { int t = __builtin_amdgcn_workgroup_id_x(); asm volatile("" : "+s"(t)); return t; }
; __device__ __forceinline__ unsigned pk2(float lo, float hi) { unsigned r; asm volatile("v_cvt_pk_bf16_f32 %0, %1, %2" : "=v"(r) : "v"(lo), "v"(hi)); return r; }
; __device__ __forceinline__ void p0_phase(const float* xin, const float* gain, bf16_t* xb) {
;     const int lane = otid() & 63; const int gw = (obid() * NTHREADS + otid()) >> 6, nw = (gridDim.x * NTHREADS) >> 6;
;     f32x4 g[4];
; #pragma unroll
;     for (int i = 0; i < 4; ++i) g[i] = *(const f32x4*)(gain + i * 256 + lane * 4);
;     for (int row = gw; row < TT; row += nw) {
;         const float* xr = xin + (size_t)row * DM; f32x4 v[4]; float ss = 0.f;
; #pragma unroll
;         for (int i = 0; i < 4; ++i) { v[i] = *(const f32x4*)(xr + i * 256 + lane * 4); ss += v[i][0] * v[i][0] + v[i][1] * v[i][1] + v[i][2] * v[i][2] + v[i][3] * v[i][3]; }
; #pragma unroll
;         for (int o = 1; o < 64; o <<= 1) ss += __shfl_xor(ss, o);
;         const float rs = rsqrtf(ss * (1.0f / DM) + 1e-6f);
; #pragma unroll
;         for (int i = 0; i < 4; ++i) { u32x2 w; w.x = pk2(v[i][0] * rs * g[i][0], v[i][1] * rs * g[i][1]); w.y = pk2(v[i][2] * rs * g[i][2], v[i][3] * rs * g[i][3]);
;             *(u32x2*)(xb + (size_t)row * DM + i * 256 + lane * 4) = w; }
;     }
.LBB0_158:
	v_readlane_b32 s36, v251, 6
	v_readlane_b32 s40, v251, 10
	v_readlane_b32 s41, v251, 11
	v_readlane_b32 s42, v251, 12
	v_readlane_b32 s43, v251, 13
	v_readlane_b32 s44, v251, 14
	v_readlane_b32 s45, v251, 15
	v_readlane_b32 s46, v251, 16
	v_readlane_b32 s47, v251, 17
	v_readlane_b32 s48, v251, 18
	v_readlane_b32 s49, v251, 19
	v_readlane_b32 s50, v251, 20
	v_readlane_b32 s51, v251, 21
	v_readlane_b32 s40, v251, 22
	v_readlane_b32 s54, v251, 36
	v_readlane_b32 s55, v251, 37
	s_cmp_eq_u32 s18, 0
	v_readlane_b32 s37, v251, 7
	s_mov_b64 s[30:31], s[54:55]
	s_cselect_b32 s1, s37, s31
	s_cselect_b32 s0, s36, s30
	v_writelane_b32 v254, s0, 36
	s_waitcnt vmcnt(0)
	v_mov_b32_e32 v20, v192
	s_waitcnt lgkmcnt(0)
	v_mov_b32_e32 v0, v192
	v_writelane_b32 v254, s1, 37
	v_readlane_b32 s0, v251, 2
	v_readlane_b32 s38, v251, 8
	v_readlane_b32 s39, v251, 9
	v_lshl_add_u32 v0, s0, 9, v0
	v_ashrrev_i32_e32 v18, 6, v0
	s_mov_b32 s0, 0x8000
	v_cmp_gt_i32_e32 vcc, s0, v18
	v_readlane_b32 s41, v251, 23
	v_readlane_b32 s42, v251, 24
	v_readlane_b32 s43, v251, 25
	v_readlane_b32 s44, v251, 26
	v_readlane_b32 s45, v251, 27
	v_readlane_b32 s46, v251, 28
	v_readlane_b32 s47, v251, 29
	v_readlane_b32 s48, v251, 30
	v_readlane_b32 s49, v251, 31
	v_readlane_b32 s50, v251, 32
	v_readlane_b32 s51, v251, 33
	v_readlane_b32 s52, v251, 34
	v_readlane_b32 s53, v251, 35
	s_and_saveexec_b64 s[0:1], vcc
	v_readlane_b32 s12, v253, 60
	v_readlane_b32 s14, v253, 62
	v_readlane_b32 s13, v253, 61
	v_readlane_b32 s15, v253, 63
	s_cbranch_execz .LBB0_161
	s_lshl_b32 s76, s18, 10
	v_readlane_b32 s36, v251, 6
	s_lshl_b64 s[10:11], s[76:77], 2
	v_readlane_b32 s38, v251, 8
	v_readlane_b32 s39, v251, 9
	s_add_u32 s10, s38, s10
	v_lshlrev_b32_e32 v0, 4, v20
	s_addc_u32 s11, s39, s11
	v_and_b32_e32 v0, 0x3f0, v0
	global_load_dwordx4 v[2:5], v0, s[10:11]
	global_load_dwordx4 v[6:9], v0, s[10:11] offset:1024
	global_load_dwordx4 v[10:13], v0, s[10:11] offset:2048
	global_load_dwordx4 v[14:17], v0, s[10:11] offset:3072
	v_xor_b32_e32 v0, 1, v197
	v_cmp_lt_i32_e32 vcc, v0, v199
	v_xor_b32_e32 v19, 2, v197
	v_and_b32_e32 v29, 63, v20
	v_cndmask_b32_e32 v0, v197, v0, vcc
	v_cmp_lt_i32_e32 vcc, v19, v199
	v_readlane_b32 s10, v251, 42
	v_readlane_b32 s11, v251, 43
	v_cndmask_b32_e32 v19, v197, v19, vcc
	v_cmp_lt_i32_e32 vcc, v250, v199
	v_lshlrev_b32_e32 v24, 2, v19
	v_lshlrev_b32_e32 v0, 2, v0
	v_cndmask_b32_e32 v19, v197, v250, vcc
	v_lshlrev_b32_e32 v25, 2, v19
	v_xor_b32_e32 v19, 8, v197
	v_cmp_lt_i32_e32 vcc, v19, v199
	s_mov_b64 s[28:29], 0
	v_readlane_b32 s37, v251, 7
	v_cndmask_b32_e32 v19, v197, v19, vcc
	v_cmp_lt_i32_e32 vcc, v204, v199
	v_lshlrev_b32_e32 v26, 2, v19
	v_readlane_b32 s40, v251, 10
	v_cndmask_b32_e32 v19, v197, v204, vcc
	v_cmp_lt_i32_e32 vcc, v205, v199
	v_lshlrev_b32_e32 v27, 2, v19
	v_readlane_b32 s41, v251, 11
	v_cndmask_b32_e32 v19, v197, v205, vcc
	v_lshlrev_b32_e32 v28, 2, v19
	v_ashrrev_i32_e32 v19, 31, v18
	v_lshlrev_b64 v[22:23], 11, v[18:19]
	v_lshl_or_b32 v22, v29, 3, v22
	v_lshl_add_u64 v[20:21], s[10:11], 0, v[22:23]
	v_lshlrev_b64 v[22:23], 12, v[18:19]
	v_readlane_b32 s10, v254, 36
	v_lshl_or_b32 v22, v29, 4, v22
	v_readlane_b32 s11, v254, 37
	v_readlane_b32 s42, v251, 12
	v_readlane_b32 s43, v251, 13
	v_lshl_add_u64 v[22:23], s[10:11], 0, v[22:23]
	s_mov_b64 s[10:11], 0xc00
	v_lshl_add_u64 v[22:23], v[22:23], 0, s[10:11]
	v_readlane_b32 s44, v251, 14
	v_readlane_b32 s45, v251, 15
	v_readlane_b32 s46, v251, 16
	v_readlane_b32 s47, v251, 17
	v_readlane_b32 s48, v251, 18
	v_readlane_b32 s49, v251, 19
	v_readlane_b32 s50, v251, 20
	v_readlane_b32 s51, v251, 21
	global_load_dwordx4 v[46:49], v[22:23], off offset:-3072
	global_load_dwordx4 v[50:53], v[22:23], off offset:-2048
	global_load_dwordx4 v[54:57], v[22:23], off offset:-1024
	global_load_dwordx4 v[58:61], v[22:23], off
	s_waitcnt vmcnt(0)
	s_branch .Lmy_p0_entry
; __device__ __forceinline__ unsigned pk2(float lo, float hi) { unsigned r; asm volatile("v_cvt_pk_bf16_f32 %0, %1, %2" : "=v"(r) : "v"(lo), "v"(hi)); return r; }
; __device__ __forceinline__ void p0_phase(const float* xin, const float* gain, bf16_t* xb) {
;     ...
;     for (int row = gw; row < TT; row += nw) {
;         const float* xr = xin + (size_t)row * DM; f32x4 v[4]; float ss = 0.f;
; #pragma unroll
;         for (int i = 0; i < 4; ++i) { v[i] = *(const f32x4*)(xr + i * 256 + lane * 4); ss += v[i][0] * v[i][0] + v[i][1] * v[i][1] + v[i][2] * v[i][2] + v[i][3] * v[i][3]; }
; #pragma unroll
;         for (int o = 1; o < 64; o <<= 1) ss += __shfl_xor(ss, o);
;         const float rs = rsqrtf(ss * (1.0f / DM) + 1e-6f);
; #pragma unroll
;         for (int i = 0; i < 4; ++i) { u32x2 w; w.x = pk2(v[i][0] * rs * g[i][0], v[i][1] * rs * g[i][1]); w.y = pk2(v[i][2] * rs * g[i][2], v[i][3] * rs * g[i][3]);
;             *(u32x2*)(xb + (size_t)row * DM + i * 256 + lane * 4) = w; }
;     }
.LBB0_160:
	s_waitcnt vmcnt(4)
.Lmy_p0_entry:
	v_mov_b64_e32 v[30:31], v[46:47]
	v_mov_b64_e32 v[32:33], v[48:49]
	v_mov_b64_e32 v[34:35], v[50:51]
	v_mov_b64_e32 v[36:37], v[52:53]
	v_mov_b64_e32 v[38:39], v[54:55]
	v_mov_b64_e32 v[40:41], v[56:57]
	v_mov_b64_e32 v[42:43], v[58:59]
	v_mov_b64_e32 v[44:45], v[60:61]
	v_add_u32_e32 v18, s25, v18
	v_cmp_lt_i32_e32 vcc, s97, v18
	s_or_b64 s[28:29], vcc, s[28:29]
	v_lshl_add_u64 v[22:23], v[22:23], 0, s[14:15]
	s_andn2_b64 vcc, exec, s[28:29]
	s_cbranch_vccz .Lmy_p0_nonext
	global_load_dwordx4 v[46:49], v[22:23], off offset:-3072
	global_load_dwordx4 v[50:53], v[22:23], off offset:-2048
	global_load_dwordx4 v[54:57], v[22:23], off offset:-1024
	global_load_dwordx4 v[58:61], v[22:23], off
.Lmy_p0_nonext:
	v_pk_mul_f32 v[24:25], v[30:31], v[30:31]
	v_pk_mul_f32 v[26:27], v[32:33], v[32:33]
	v_pk_fma_f32 v[24:25], v[34:35], v[34:35], v[24:25]
	v_pk_fma_f32 v[26:27], v[36:37], v[36:37], v[26:27]
	v_pk_fma_f32 v[24:25], v[38:39], v[38:39], v[24:25]
	v_pk_fma_f32 v[26:27], v[40:41], v[40:41], v[26:27]
	v_pk_fma_f32 v[24:25], v[42:43], v[42:43], v[24:25]
	v_pk_fma_f32 v[26:27], v[44:45], v[44:45], v[26:27]
	v_pk_add_f32 v[24:25], v[24:25], v[26:27]
	s_nop 0
	v_add_f32_e32 v19, v24, v25
	s_nop 1
	v_add_f32_dpp v19, v19, v19 quad_perm:[1,0,3,2] row_mask:0xf bank_mask:0xf
	s_nop 1
	v_add_f32_dpp v19, v19, v19 quad_perm:[2,3,0,1] row_mask:0xf bank_mask:0xf
	s_nop 1
	v_add_f32_dpp v19, v19, v19 row_half_mirror row_mask:0xf bank_mask:0xf
	s_nop 1
	v_add_f32_dpp v19, v19, v19 row_mirror row_mask:0xf bank_mask:0xf
	v_mov_b32_e32 v29, v19
	s_nop 1
	v_permlane16_swap_b32_e32 v19, v29
	v_add_f32_e32 v19, v19, v29
	v_mov_b32_e32 v29, v19
	s_nop 1
	v_permlane32_swap_b32_e32 v19, v29
	v_add_f32_e32 v19, v19, v29
	v_fmamk_f32 v19, v19, 0x3a800000, v193
	v_mul_f32_e32 v29, 0x4b800000, v19
	v_cmp_gt_f32_e32 vcc, s68, v19
	s_nop 1
	v_cndmask_b32_e32 v19, v19, v29, vcc
	v_rsq_f32_e32 v19, v19
	s_nop 0
	v_mul_f32_e32 v29, 0x45800000, v19
	v_cndmask_b32_e32 v19, v19, v29, vcc
	v_mul_f32_e32 v29, v30, v19
	v_mul_f32_e32 v30, v31, v19
	v_mul_f32_e32 v31, v32, v19
	v_mul_f32_e32 v32, v33, v19
	v_mul_f32_e32 v30, v3, v30
	v_mul_f32_e32 v31, v4, v31
	v_mul_f32_e32 v33, v34, v19
	v_mul_f32_e32 v34, v35, v19
	v_mul_f32_e32 v35, v36, v19
	v_mul_f32_e32 v36, v37, v19
	v_mul_f32_e32 v29, v2, v29
	v_mul_f32_e32 v32, v5, v32
	v_cvt_pk_bf16_f32 v30, v29, v30
	v_cvt_pk_bf16_f32 v31, v31, v32
	v_mul_f32_e32 v37, v38, v19
	v_mul_f32_e32 v38, v39, v19
	v_mul_f32_e32 v39, v40, v19
	v_mul_f32_e32 v40, v41, v19
	v_mul_f32_e32 v33, v6, v33
	v_mul_f32_e32 v34, v7, v34
	v_mul_f32_e32 v35, v8, v35
	v_mul_f32_e32 v36, v9, v36
	global_store_dwordx2 v[20:21], v[30:31], off
	v_cvt_pk_bf16_f32 v30, v33, v34
	v_cvt_pk_bf16_f32 v31, v35, v36
	v_mul_f32_e32 v41, v42, v19
	v_mul_f32_e32 v42, v43, v19
	v_mul_f32_e32 v43, v44, v19
	v_mul_f32_e32 v19, v45, v19
	v_mul_f32_e32 v37, v10, v37
	v_mul_f32_e32 v38, v11, v38
	v_mul_f32_e32 v39, v12, v39
	v_mul_f32_e32 v40, v13, v40
	global_store_dwordx2 v[20:21], v[30:31], off offset:512
	v_cvt_pk_bf16_f32 v30, v37, v38
	v_cvt_pk_bf16_f32 v31, v39, v40
	v_mul_f32_e32 v41, v14, v41
	v_mul_f32_e32 v42, v15, v42
	v_mul_f32_e32 v43, v16, v43
	v_mul_f32_e32 v19, v17, v19
	global_store_dwordx2 v[20:21], v[30:31], off offset:1024
	v_cvt_pk_bf16_f32 v30, v41, v42
	v_cvt_pk_bf16_f32 v31, v43, v19
	global_store_dwordx2 v[20:21], v[30:31], off offset:1536
	v_lshl_add_u64 v[20:21], v[20:21], 0, s[12:13]
	s_andn2_b64 exec, exec, s[28:29]
	s_cbranch_execnz .LBB0_160
